# MLA loop restructure variant: K/V tile global loads issued one phase earlier (right after the LDS staging stores)
# speedup vs baseline: 1.0212x; 1.0212x over previous
; #define ATT_LBAR() asm volatile("s_waitcnt lgkmcnt(0)\n\ts_barrier" ::: "memory")
; template <int MODE> DI void attn_unit(int b, int qb, const bf16* Qb, int qpitch, const bf16* Kb, int kpitch, const bf16* VT, bf16* O, float* ssq, ...
;     ...
;     ATT_LOAD(REV ? kt_hi : kt_lo); ATT_STORE(0);
;     ATT_LBAR();
;     float m = (MODE == 0) ? aux2[0] * LOG2E : NEGBIG;
;     float lsum = (MODE == 0 && hi == 0) ? 1.f : 0.f;
;     v16f o0 = {}, o1 = {};
;     int buf = 0;
;     bool seen = false;
;     for (int it = 0; it < ntile; ++it) {
;         const int kt = REV ? kt_hi - it : kt_lo + it;
;         const bool more = it + 1 < ntile;
;         if (more) ATT_LOAD(REV ? kt - 1 : kt + 1);
.Lmla_p2:
	s_or_b64 exec, exec, s[18:19]
	v_add_u32_e32 v0, 0x6800, v192
	ds_write2_b64 v0, v[98:99], v[100:101] offset1:1
	s_waitcnt lgkmcnt(0)
	s_barrier
	v_mov_b32_e32 v14, v65
	v_mov_b32_e32 v15, v65
	s_lshl_b32 s60, s24, 2
	v_mov_b32_e32 v0, v65
	v_mov_b32_e32 v1, v65
	v_mov_b32_e32 v2, v65
	v_mov_b32_e32 v3, v65
	v_mov_b32_e32 v4, v65
	v_mov_b32_e32 v5, v65
	v_mov_b32_e32 v6, v65
	v_mov_b32_e32 v7, v65
	v_mov_b32_e32 v8, v65
	v_mov_b32_e32 v9, v65
	v_mov_b32_e32 v10, v65
	v_mov_b32_e32 v11, v65
	v_mov_b32_e32 v12, v65
	v_mov_b32_e32 v13, v65
	v_mov_b64_e32 v[30:31], v[14:15]
	s_xor_b64 s[18:19], s[22:23], -1
	s_add_i32 s60, s60, 4
	s_or_b32 s61, s59, 31
	s_addk_i32 s69, 0x100
	s_mov_b32 s72, 0
	v_mov_b32_e32 v157, 0xf149f2ca
	v_mov_b32_e32 v155, 0
	s_mov_b32 s74, 1
	v_lshl_add_u64 v[184:185], v[180:181], 0, s[80:81]
	v_lshl_add_u64 v[186:187], v[178:179], 0, s[80:81]
	v_mov_b64_e32 v[188:189], v[176:177]
	v_mov_b64_e32 v[28:29], v[12:13]
	v_mov_b64_e32 v[26:27], v[10:11]
	v_mov_b64_e32 v[24:25], v[8:9]
	v_mov_b64_e32 v[22:23], v[6:7]
	v_mov_b64_e32 v[20:21], v[4:5]
	v_mov_b64_e32 v[18:19], v[2:3]
	v_mov_b64_e32 v[16:17], v[0:1]
	s_mov_b32 s75, 0
	s_mov_b32 s98, 0x680000
	s_mov_b32 s99, 0x8a3400
	s_mov_b32 s100, 0x190b800
	s_mov_b32 s101, 0
	s_add_i32 s24, s74, 1
	s_cmp_lt_u32 s24, s60
	s_cselect_b64 s[22:23], -1, 0
	s_cbranch_scc0 .Lmla_nok_p
	global_load_dwordx4 v[90:93], v[184:185], off
	s_and_saveexec_b64 s[24:25], s[38:39]
	s_cbranch_execz .Lmla_k1_p
	global_load_dwordx4 v[94:97], v[186:187], off

; template <int MODE> DI void attn_unit(int b, int qb, const bf16* Qb, int qpitch, const bf16* Kb, int kpitch, const bf16* VT, bf16* O, float* ssq, ...
;     ...
;     for (int it = 0; it < ntile; ++it) {
;         const int kt = REV ? kt_hi - it : kt_lo + it;
;         const bool more = it + 1 < ntile;
;         if (more) ATT_LOAD(REV ? kt - 1 : kt + 1);
.Lmla_nov_p:
	s_cmp_lt_u32 s33, 4
	s_cbranch_scc1 .Lmla_loop
	s_barrier

; template <int MODE> DI void attn_unit(int b, int qb, const bf16* Qb, int qpitch, const bf16* Kb, int kpitch, const bf16* VT, bf16* O, float* ssq, ...
;     ...
;     for (int it = 0; it < ntile; ++it) {
;         const int kt = REV ? kt_hi - it : kt_lo + it;
;         const bool more = it + 1 < ntile;
;         if (more) ATT_LOAD(REV ? kt - 1 : kt + 1);
.Lmla_nostv:
	s_add_i32 s72, s72, 64
	s_add_i32 s74, s74, 1
	v_lshl_add_u64 v[188:189], v[188:189], 0, s[92:93]
	v_lshl_add_u64 v[186:187], v[186:187], 0, s[80:81]
	v_lshl_add_u64 v[184:185], v[184:185], 0, s[80:81]
	s_mov_b32 s24, s98
	s_mov_b32 s98, s99
	s_mov_b32 s99, s100
	s_mov_b32 s100, s24
	s_add_i32 s24, s74, 1
	s_cmp_lt_u32 s24, s60
	s_cselect_b64 s[22:23], -1, 0
	s_cbranch_scc0 .Lmla_nok_e
	global_load_dwordx4 v[90:93], v[184:185], off
	s_and_saveexec_b64 s[24:25], s[38:39]
	s_cbranch_execz .Lmla_k1_e
	global_load_dwordx4 v[94:97], v[186:187], off

; #define LAS __attribute__((address_space(3)))
; DI unsigned pk2(float lo, float hi) { f32x2_t v = {lo, hi}; bf16x2_t b = __builtin_convertvector(v, bf16x2_t); return __builtin_bit_cast(unsigned, b); }
; template <int MODE> DI void attn_unit(int b, int qb, const bf16* Qb, int qpitch, const bf16* Kb, int kpitch, const bf16* VT, bf16* O, float* ssq, ...
;     ...
;             const LAS unsigned char* vb = lds + VOFF + buf * VSZ + r32 * 136 + 8 * hi;
; #pragma unroll
;             for (int s4 = 0; s4 < 4; ++s4) {
;                 v4u pw;
;                 if (s4 == 0) { pw.x = pk2(p0[0], p0[1]); pw.y = pk2(p0[2], p0[3]); pw.z = pk2(p0[4], p0[5]); pw.w = pk2(p0[6], p0[7]); }
;                 if (s4 == 1) { pw.x = pk2(p0[8], p0[9]); pw.y = pk2(p0[10], p0[11]); pw.z = pk2(p0[12], p0[13]); pw.w = pk2(p0[14], p0[15]); }
;                 if (s4 == 2) { pw.x = pk2(p1[0], p1[1]); pw.y = pk2(p1[2], p1[3]); pw.z = pk2(p1[4], p1[5]); pw.w = pk2(p1[6], p1[7]); }
;                 if (s4 == 3) { pw.x = pk2(p1[8], p1[9]); pw.y = pk2(p1[10], p1[11]); pw.z = pk2(p1[12], p1[13]); pw.w = pk2(p1[14], p1[15]); }
;                 const v8s pf = __builtin_bit_cast(v8s, pw);
;                 const v2u a0 = *(const LAS v2u*)(vb + 32 * s4), a1 = *(const LAS v2u*)(vb + 32 * s4 + 16);
;                 const v2u c0 = *(const LAS v2u*)(vb + 32 * 136 + 32 * s4), c1 = *(const LAS v2u*)(vb + 32 * 136 + 32 * s4 + 16);
;                 const v4u va = {a0.x, a0.y, a1.x, a1.y}, vc2 = {c0.x, c0.y, c1.x, c1.y};
;                 o0 = MFMA32(__builtin_bit_cast(v8s, va), pf, o0);
;                 o1 = MFMA32(__builtin_bit_cast(v8s, vc2), pf, o1);
;             }
;         }
;         if (more) ATT_STORE(buf ^ 1);
;         if (REV) {
;             int vote = 0;
;             if (seen && kt > 0) { const float fb0 = ((const LAS float*)(lds + FOFF + buf * 256))[0]; const float kb = MS[32 + ((kt - 1) >> 1)]; vote = __all((qn * kb + fb0 - m) < -40.0f) ? 1 : 0; }
;             volatile LAS int* vt = (volatile LAS int*)(MS + 64) + (it & 1) * 8;
;             if (lane == 0) vt[wave] = vote;
;             __syncthreads();
;             const int stop = vt[0] & vt[1] & vt[2] & vt[3] & vt[4] & vt[5] & vt[6] & vt[7];
;             if (stop) break;
;         } else {
;             __syncthreads();
;         }
;         buf ^= 1;
;     }
.Lmla_nov_e:
	s_cmp_eq_u32 s69, s72
	s_waitcnt lgkmcnt(0)
	s_barrier
	s_cbranch_scc0 .Lmla_loop
	s_cmp_eq_u32 s101, 0
	s_cbranch_scc1 .Lmla_nopv2
	s_lshr_b32 s24, s100, 8
	s_and_b32 s24, s24, 0xffffff00
	v_add_u32_e32 v41, s24, v195
	v_add_u32_e32 v62, 0x1000, v41
	ds_read2_b64 v[50:53], v41 offset1:2
	ds_read2_b64 v[54:57], v41 offset0:4 offset1:6
	ds_read2_b64 v[58:61], v62 offset0:32 offset1:34
	s_waitcnt lgkmcnt(2)
	v_mfma_f32_32x32x16_bf16 v[0:15], v[50:53], v[42:45], v[0:15]
	s_waitcnt lgkmcnt(0)
	v_mfma_f32_32x32x16_bf16 v[16:31], v[58:61], v[42:45], v[16:31]
	ds_read2_b64 v[42:45], v62 offset0:36 offset1:38
	v_mfma_f32_32x32x16_bf16 v[0:15], v[54:57], v[46:49], v[0:15]
	s_waitcnt lgkmcnt(0)
	v_mfma_f32_32x32x16_bf16 v[16:31], v[42:45], v[46:49], v[16:31]
	ds_read2_b64 v[42:45], v41 offset0:8 offset1:10
	ds_read2_b64 v[46:49], v62 offset0:40 offset1:42
	s_waitcnt lgkmcnt(1)
	v_mfma_f32_32x32x16_bf16 v[0:15], v[42:45], v[36:39], v[0:15]
	s_waitcnt lgkmcnt(0)
	v_mfma_f32_32x32x16_bf16 v[16:31], v[46:49], v[36:39], v[16:31]
	ds_read2_b64 v[36:39], v41 offset0:12 offset1:14
	ds_read2_b64 v[42:45], v62 offset0:44 offset1:46
	s_waitcnt lgkmcnt(1)
	v_mfma_f32_32x32x16_bf16 v[0:15], v[36:39], v[32:35], v[0:15]
	s_waitcnt lgkmcnt(0)
	v_mfma_f32_32x32x16_bf16 v[16:31], v[42:45], v[32:35], v[16:31]
	s_nop 7
	s_nop 3
